# N2 norm loop: next row prefetched into spare registers while the current row is reduced/scaled/stored; counted vmcnt so the row's stores are not waited on
# baseline (speedup 1.0000x reference)
.LBB0_75:
	s_andn2_b64 vcc, exec, s[0:1]
	s_cbranch_vccnz .LBB0_109
	s_cmp_gt_i32 s28, 4
	s_mov_b64 s[0:1], -1
	s_cbranch_scc0 .LBB0_83
	v_readlane_b32 s1, v252, 4
	s_mul_i32 s0, s1, s27
	s_add_i32 s1, s0, s1
	s_min_i32 s2, s1, 0x8000
	v_mov_b32_e32 v2, v207
	s_cmp_ge_i32 s0, s2
	s_cbranch_scc1 .LBB0_82
	v_readlane_b32 s8, v252, 34
	v_and_b32_e32 v1, 64, v203
	v_readlane_b32 s9, v252, 35
	s_mov_b32 s4, s8
	v_add_u32_e32 v1, 64, v1
	v_xor_b32_e32 v4, 1, v203
	s_mov_b32 s9, s5
	v_writelane_b32 v252, s4, 34
	v_cmp_lt_i32_e32 vcc, v4, v1
	s_mov_b32 s3, s56
	v_writelane_b32 v252, s5, 35
	v_cndmask_b32_e32 v4, v203, v4, vcc
	v_readlane_b32 s1, v252, 31
	s_mov_b32 s4, s57
	v_readlane_b32 s44, v253, 8
	v_lshlrev_b32_e32 v54, 2, v4
	v_xor_b32_e32 v4, 2, v203
	s_lshl_b64 s[12:13], s[8:9], 12
	s_lshl_b32 s1, s1, 12
	v_readlane_b32 s54, v253, 18
	v_cmp_lt_i32_e32 vcc, v4, v1
	v_readlane_b32 s55, v253, 19
	s_add_u32 s14, s54, s1
	v_cndmask_b32_e32 v4, v203, v4, vcc
	v_readlane_b32 s56, v253, 20
	s_addc_u32 s15, s55, 0
	v_readlane_b32 s1, v252, 28
	v_lshlrev_b32_e32 v55, 2, v4
	v_xor_b32_e32 v4, 4, v203
	v_readlane_b32 s57, v253, 21
	s_mov_b32 s56, s3
	s_add_u32 s3, s1, 0x3000
	v_readlane_b32 s1, v252, 29
	v_cmp_lt_i32_e32 vcc, v4, v1
	s_mov_b32 s57, s4
	s_addc_u32 s4, s1, 0
	v_cndmask_b32_e32 v4, v203, v4, vcc
	v_readlane_b32 s1, v252, 5
	v_lshlrev_b32_e32 v56, 2, v4
	v_xor_b32_e32 v4, 8, v203
	s_mul_i32 s1, s1, s27
	v_lshlrev_b32_e32 v16, 2, v2
	v_cmp_lt_i32_e32 vcc, v4, v1
	s_addk_i32 s1, 0x600
	v_ashrrev_i32_e32 v17, 31, v16
	v_cndmask_b32_e32 v4, v203, v4, vcc
	v_lshl_add_u32 v60, v2, 3, s1
	s_ashr_i32 s1, s0, 31
	v_lshlrev_b32_e32 v57, 2, v4
	v_xor_b32_e32 v4, 16, v203
	v_lshl_add_u64 v[42:43], v[16:17], 2, s[14:15]
	s_lshl_b64 s[14:15], s[0:1], 12
	v_cmp_lt_i32_e32 vcc, v4, v1
	s_add_u32 s1, s14, s12
	s_addc_u32 s9, s15, s13
	v_cndmask_b32_e32 v4, v203, v4, vcc
	v_readlane_b32 s12, v252, 6
	v_lshlrev_b32_e32 v58, 2, v4
	v_xor_b32_e32 v4, 32, v203
	s_add_u32 s12, s12, s1
	v_readlane_b32 s1, v252, 7
	v_ashrrev_i32_e32 v3, 31, v2
	v_cmp_lt_i32_e32 vcc, v4, v1
	s_addc_u32 s13, s1, s9
	v_lshl_add_u64 v[50:51], v[2:3], 4, s[12:13]
	v_cndmask_b32_e32 v1, v203, v4, vcc
	v_mov_b32_e32 v2, v0
	v_mov_b32_e32 v3, v0
	v_mov_b32_e32 v4, v0
	v_mov_b32_e32 v5, v0
	v_mov_b32_e32 v6, v0
	v_mov_b32_e32 v7, v0
	v_mov_b32_e32 v8, v0
	v_mov_b32_e32 v9, v0
	v_mov_b32_e32 v10, v0
	v_mov_b32_e32 v11, v0
	v_mov_b32_e32 v12, v0
	v_mov_b32_e32 v13, v0
	v_mov_b32_e32 v14, v0
	v_mov_b32_e32 v15, v0
	v_mov_b32_e32 v30, v0
	v_mov_b32_e32 v31, v0
	v_readlane_b32 s52, v253, 16
	v_readlane_b32 s53, v253, 17
	v_readlane_b32 s54, v252, 22
	v_lshlrev_b32_e32 v59, 2, v1
	v_add_u32_e32 v44, 0x100, v16
	v_add_u32_e32 v46, 0x200, v16
	v_add_u32_e32 v48, 0x300, v16
	v_mov_b32_e32 v1, v0
	v_mov_b32_e32 v32, v0
	v_mov_b32_e32 v33, v0
	v_lshlrev_b64 v[52:53], 2, v[16:17]
	v_mov_b64_e32 v[26:27], v[30:31]
	v_mov_b64_e32 v[22:23], v[30:31]
	v_mov_b64_e32 v[18:19], v[30:31]
	v_mov_b64_e32 v[16:17], v[14:15]
	s_mov_b64 s[20:21], 0x1000
	v_readlane_b32 s53, v252, 17
	v_readlane_b32 s52, v252, 16
	v_readlane_b32 s55, v252, 23
	s_mov_b32 s8, -1
	v_ashrrev_i32_e32 v45, 31, v44
	v_ashrrev_i32_e32 v47, 31, v46
	v_ashrrev_i32_e32 v49, 31, v48
	v_mov_b64_e32 v[28:29], v[32:33]
	v_mov_b64_e32 v[24:25], v[32:33]
	v_mov_b64_e32 v[20:21], v[32:33]
	v_mov_b64_e32 v[14:15], v[12:13]
	v_mov_b64_e32 v[12:13], v[10:11]
	v_mov_b64_e32 v[10:11], v[8:9]
	v_mov_b64_e32 v[8:9], v[6:7]
	v_mov_b64_e32 v[6:7], v[4:5]
	v_mov_b64_e32 v[4:5], v[2:3]
	v_mov_b64_e32 v[2:3], v[0:1]
	v_readlane_b32 s45, v253, 9
	v_readlane_b32 s46, v253, 10
	v_readlane_b32 s47, v253, 11
	v_readlane_b32 s48, v253, 12
	v_readlane_b32 s49, v253, 13
	v_readlane_b32 s50, v253, 14
	v_readlane_b32 s51, v253, 15
	v_readlane_b32 s58, v253, 22
	v_readlane_b32 s59, v253, 23
	global_load_dwordx4 v[90:93], v[50:51], off offset:-3072
	global_load_dwordx4 v[94:97], v[50:51], off offset:-2048
	global_load_dwordx4 v[98:101], v[50:51], off offset:-1024
	global_load_dwordx4 v[102:105], v[50:51], off
	s_waitcnt vmcnt(0)
	s_branch .LBB0_80
.LBB0_79:
	s_waitcnt vmcnt(4)
	v_mov_b64_e32 v[62:63], v[90:91]
	v_mov_b64_e32 v[64:65], v[92:93]
	v_mov_b64_e32 v[66:67], v[94:95]
	v_mov_b64_e32 v[68:69], v[96:97]
	v_mov_b64_e32 v[84:85], v[98:99]
	v_mov_b64_e32 v[86:87], v[100:101]
	v_mov_b64_e32 v[80:81], v[102:103]
	v_mov_b64_e32 v[82:83], v[104:105]
	s_add_i32 s0, s0, 1
	v_lshl_add_u64 v[50:51], v[50:51], 0, s[20:21]
	s_cmp_ge_i32 s0, s2
	s_cbranch_scc1 .Ln2_nopf
	global_load_dwordx4 v[90:93], v[50:51], off offset:-3072
	global_load_dwordx4 v[94:97], v[50:51], off offset:-2048
	global_load_dwordx4 v[98:101], v[50:51], off offset:-1024
	global_load_dwordx4 v[102:105], v[50:51], off
.Ln2_nopf:
	v_readlane_b32 s12, v252, 0
	v_readlane_b32 s13, v252, 1
	v_readlane_b32 s14, v252, 2
	v_readlane_b32 s15, v252, 3
	s_cmp_ge_i32 s0, s2
	v_pk_mul_f32 v[34:35], v[64:65], v[64:65]
	v_pk_mul_f32 v[36:37], v[62:63], v[62:63]
	s_nop 0
	v_pk_mov_b32 v[38:39], v[36:37], v[34:35] op_sel:[1,0]
	v_mov_b32_e32 v37, v35
	v_pk_add_f32 v[70:71], v[38:39], v[36:37]
	v_pk_mul_f32 v[34:35], v[68:69], v[68:69]
	v_pk_mul_f32 v[36:37], v[66:67], v[66:67]
	v_pk_add_f32 v[70:71], v[70:71], v[70:71] op_sel:[0,1] op_sel_hi:[1,0]
	v_pk_mov_b32 v[38:39], v[36:37], v[34:35] op_sel:[1,0]
	v_mov_b32_e32 v37, v35
	v_pk_add_f32 v[72:73], v[38:39], v[36:37]
	v_pk_add_f32 v[72:73], v[72:73], v[72:73] op_sel:[0,1] op_sel_hi:[1,0]
	v_mul_f32_e32 v1, v80, v80
	v_mul_f32_e32 v61, v81, v81
	v_mov_b32_e32 v71, v1
	v_mov_b32_e32 v73, v61
	v_pk_add_f32 v[70:71], v[70:71], v[72:73]
	v_mul_f32_e32 v72, v85, v85
	v_mul_f32_e32 v74, v82, v82
	v_pk_fma_f32 v[72:73], v[84:85], v[84:85], v[72:73] op_sel_hi:[1,1,0]
	v_mul_f32_e32 v76, v83, v83
	v_mov_b32_e32 v73, v74
	v_mul_f32_e32 v74, v87, v87
	v_pk_fma_f32 v[74:75], v[86:87], v[86:87], v[74:75] op_sel_hi:[1,1,0]
	s_nop 0
	v_mov_b32_e32 v75, v76
	v_pk_add_f32 v[72:73], v[72:73], v[74:75]
	s_nop 0
	v_pk_add_f32 v[70:71], v[70:71], v[72:73]
	s_nop 0
	v_add_f32_e32 v1, v70, v71
	ds_bpermute_b32 v61, v54, v1
	s_waitcnt lgkmcnt(0)
	v_add_f32_e32 v1, v1, v61
	ds_bpermute_b32 v61, v55, v1
	s_waitcnt lgkmcnt(0)
	v_add_f32_e32 v1, v1, v61
	ds_bpermute_b32 v61, v56, v1
	s_waitcnt lgkmcnt(0)
	v_add_f32_e32 v1, v1, v61
	ds_bpermute_b32 v61, v57, v1
	s_waitcnt lgkmcnt(0)
	v_add_f32_e32 v1, v1, v61
	ds_bpermute_b32 v61, v58, v1
	s_waitcnt lgkmcnt(0)
	v_add_f32_e32 v1, v1, v61
	ds_bpermute_b32 v61, v59, v1
	s_waitcnt lgkmcnt(0)
	v_add_f32_e32 v1, v1, v61
	v_fmamk_f32 v1, v1, 0x3a800000, v201
	v_rsq_f32_e32 v70, v1
	v_add_u32_e32 v1, 0xfffffa00, v60
	v_pk_mul_f32 v[62:63], v[62:63], v[70:71] op_sel_hi:[1,0]
	v_pk_mul_f32 v[64:65], v[64:65], v[70:71] op_sel_hi:[1,0]
	v_pk_fma_f32 v[62:63], v[2:3], v[62:63], v[18:19]
	v_pk_fma_f32 v[64:65], v[4:5], v[64:65], v[20:21]
	v_cvt_pk_bf16_f32 v62, v62, v63
	v_cvt_pk_bf16_f32 v63, v64, v65
	buffer_store_dwordx2 v[62:63], v1, s[12:15], 0 offen sc1
	v_pk_mul_f32 v[62:63], v[66:67], v[70:71] op_sel_hi:[1,0]
	v_pk_mul_f32 v[64:65], v[68:69], v[70:71] op_sel_hi:[1,0]
	v_pk_fma_f32 v[62:63], v[6:7], v[62:63], v[22:23]
	v_pk_fma_f32 v[64:65], v[8:9], v[64:65], v[24:25]
	v_pk_mul_f32 v[84:85], v[84:85], v[70:71] op_sel_hi:[1,0]
	v_pk_mul_f32 v[86:87], v[86:87], v[70:71] op_sel_hi:[1,0]
	v_pk_mul_f32 v[80:81], v[80:81], v[70:71] op_sel_hi:[1,0]
	v_pk_mul_f32 v[82:83], v[82:83], v[70:71] op_sel_hi:[1,0]
	v_cvt_pk_bf16_f32 v62, v62, v63
	v_cvt_pk_bf16_f32 v63, v64, v65
	v_add_u32_e32 v1, 0xfffffc00, v60
	v_pk_fma_f32 v[86:87], v[12:13], v[86:87], v[28:29]
	v_pk_fma_f32 v[84:85], v[10:11], v[84:85], v[26:27]
	v_pk_fma_f32 v[82:83], v[16:17], v[82:83], v[32:33]
	v_pk_fma_f32 v[80:81], v[14:15], v[80:81], v[30:31]
	buffer_store_dwordx2 v[62:63], v1, s[12:15], 0 offen sc1
	v_cvt_pk_bf16_f32 v84, v84, v85
	v_cvt_pk_bf16_f32 v85, v86, v87
	v_add_u32_e32 v1, 0xfffffe00, v60
	v_cvt_pk_bf16_f32 v80, v80, v81
	v_cvt_pk_bf16_f32 v81, v82, v83
	buffer_store_dwordx2 v[84:85], v1, s[12:15], 0 offen sc1
	buffer_store_dwordx2 v[80:81], v60, s[12:15], 0 offen sc1
	v_add_u32_e32 v60, 0x800, v60
	s_cbranch_scc1 .LBB0_82
.LBB0_80:
	v_readlane_b32 s12, v252, 34
	s_add_i32 s1, s12, s0
	s_add_i32 s12, s1, 0xffff8000
	s_lshr_b32 s12, s12, 13
	s_ashr_i32 s9, s1, 11
	s_add_i32 s12, s12, 16
	s_cmp_lt_i32 s1, 0x8000
	s_cselect_b32 s1, s9, s12
	s_cmp_eq_u32 s1, s8
	v_readlane_b32 s13, v252, 35
	s_cbranch_scc1 .LBB0_79
	s_mul_i32 s8, s1, 0x6000
	s_mul_hi_i32 s9, s1, 0x6000
	s_add_u32 s8, s3, s8
	s_addc_u32 s9, s4, s9
	s_add_u32 s12, s8, 0x1000
	s_addc_u32 s13, s9, 0
	v_lshl_add_u64 v[6:7], s[12:13], 0, v[52:53]
	v_lshl_add_u64 v[66:67], s[8:9], 0, v[52:53]
	v_lshl_add_u64 v[10:11], v[44:45], 2, s[12:13]
	v_lshl_add_u64 v[14:15], v[46:47], 2, s[12:13]
	v_lshl_add_u64 v[62:63], v[48:49], 2, s[12:13]
	global_load_dwordx4 v[2:5], v[42:43], off
	s_mov_b32 s8, s1
	global_load_dwordx4 v[6:9], v[6:7], off
	s_nop 0
	global_load_dwordx4 v[18:21], v[66:67], off
	global_load_dwordx4 v[30:33], v[42:43], off offset:1024
	s_nop 0
	global_load_dwordx4 v[10:13], v[10:11], off
	s_nop 0
	global_load_dwordx4 v[22:25], v[66:67], off offset:1024
	global_load_dwordx4 v[34:37], v[42:43], off offset:2048
	s_nop 0
	global_load_dwordx4 v[14:17], v[14:15], off
	s_nop 0
	global_load_dwordx4 v[26:29], v[66:67], off offset:2048
	global_load_dwordx4 v[38:41], v[42:43], off offset:3072
	s_waitcnt vmcnt(0)
	v_pk_add_f32 v[68:69], v[8:9], 1.0 op_sel_hi:[1,0]
	global_load_dwordx4 v[62:65], v[62:63], off
	v_pk_add_f32 v[8:9], v[12:13], 1.0 op_sel_hi:[1,0]
	v_pk_add_f32 v[12:13], v[16:17], 1.0 op_sel_hi:[1,0]
	v_pk_mul_f32 v[8:9], v[32:33], v[8:9]
	v_pk_mul_f32 v[12:13], v[36:37], v[12:13]
	v_pk_mul_f32 v[4:5], v[4:5], v[68:69]
	s_waitcnt vmcnt(0)
	v_pk_add_f32 v[16:17], v[64:65], 1.0 op_sel_hi:[1,0]
	v_pk_add_f32 v[64:65], v[6:7], 1.0 op_sel_hi:[1,0]
	v_pk_add_f32 v[6:7], v[10:11], 1.0 op_sel_hi:[1,0]
	v_pk_add_f32 v[10:11], v[14:15], 1.0 op_sel_hi:[1,0]
	v_pk_mul_f32 v[6:7], v[30:31], v[6:7]
	global_load_dwordx4 v[30:33], v[66:67], off offset:3072
	v_pk_add_f32 v[14:15], v[62:63], 1.0 op_sel_hi:[1,0]
	v_pk_mul_f32 v[16:17], v[40:41], v[16:17]
	v_pk_mul_f32 v[14:15], v[38:39], v[14:15]
	v_pk_mul_f32 v[10:11], v[34:35], v[10:11]
	v_pk_mul_f32 v[2:3], v[2:3], v[64:65]
	s_waitcnt vmcnt(0)
	s_branch .LBB0_79
